# P5 epilogue residual loads 3 batches deep (third register set = the mainloop's B-fragment registers, dead in the epilogue); otherwise v69
# speedup vs baseline: 1.0233x; 1.0233x over previous
;     __device__ __forceinline__ void operator()(f32x4 (&acc)[2][2][4][2], const Unit& u, int wr, int wc, int fr, int fq, LAS unsigned char* lds) const {
;     ...
;             const float* gr = gatef + (u.pm >> 3) * DM + col0;
;             f32x4 gv[2][2];
; #pragma unroll
;             for (int bj = 0; bj < 2; ++bj) { gv[bj][0] = *(const f32x4*)(gr + bj * HALF); gv[bj][1] = *(const f32x4*)(gr + bj * HALF + 4); }
; #pragma unroll
;             for (int ai = 0; ai < 2; ++ai)
; #pragma unroll
;                 for (int m = 0; m < 4; ++m) { int rr_ = row0 + ai * HALF + m * 16; asm volatile("" : "+v"(rr_)); const float* xr = xp + (size_t)rr_ * DM + col0;
;                     float sq = 0.f;
; #pragma unroll
;                     for (int bj = 0; bj < 2; ++bj) { const f32x4 v0 = *(const f32x4*)(xr + bj * HALF) + gv[bj][0] * acc[ai][bj][m][0], v1 = *(const f32x4*)(xr + bj * HALF + 4) + gv[bj][1] * acc[ai][bj][m][1];
;                         acc[ai][bj][m][0] = v0; acc[ai][bj][m][1] = v1;
;                         sq += ((v0[0] * v0[0] + v0[1] * v0[1]) + (v0[2] * v0[2] + v0[3] * v0[3])) + ((v1[0] * v1[0] + v1[1] * v1[1]) + (v1[2] * v1[2] + v1[3] * v1[3])); }
;                     sq += __shfl_xor(sq, 16); sq += __shfl_xor(sq, 32);
;                     if (fq == 0) P[(ai * HALF + wr * 64 + m * 16 + fr) * 4 + wc] = sq; }
.LBB0_1217:
	s_lshl_b32 s4, s73, 8
	s_add_i32 s16, s4, s62
	s_lshl_b32 s4, s73, 7
	s_and_b32 s4, s4, 0xfffffc00
	v_mov_b32_e32 v160, v180
	s_ashr_i32 s5, s4, 31
	s_lshl_b64 s[4:5], s[4:5], 2
	v_bfe_u32 v190, v160, 4, 2
	v_and_b32_e32 v159, 15, v160
	v_lshl_or_b32 v116, v190, 3, s68
	s_add_u32 s4, s22, s4
	v_or_b32_e32 v158, s16, v159
	s_addc_u32 s5, s23, s5
	v_lshlrev_b32_e32 v152, 2, v116
	v_mov_b32_e32 v162, v158
	global_load_dwordx4 v[128:131], v152, s[4:5] offset:16
	global_load_dwordx4 v[132:135], v152, s[4:5]
	global_load_dwordx4 v[116:119], v152, s[4:5] offset:528
	global_load_dwordx4 v[124:127], v152, s[4:5] offset:512
	v_xor_b32_e32 v161, 16, v176
	v_ashrrev_i32_e32 v163, 31, v162
	v_lshlrev_b64 v[162:163], 12, v[162:163]
	v_lshl_add_u64 v[162:163], s[36:37], 0, v[162:163]
	v_lshl_add_u64 v[174:175], v[162:163], 0, v[152:153]
	global_load_dwordx4 v[218:221], v[174:175], off
	global_load_dwordx4 v[222:225], v[174:175], off offset:16
	global_load_dwordx4 v[226:229], v[174:175], off offset:512
	global_load_dwordx4 v[230:233], v[174:175], off offset:528
	v_add_u32_e32 v250, 16, v158
	v_ashrrev_i32_e32 v251, 31, v250
	v_lshlrev_b64 v[250:251], 12, v[250:251]
	v_lshl_add_u64 v[250:251], s[36:37], 0, v[250:251]
	v_lshl_add_u64 v[250:251], v[250:251], 0, v[152:153]
	global_load_dwordx4 v[234:237], v[250:251], off
	global_load_dwordx4 v[238:241], v[250:251], off offset:16
	global_load_dwordx4 v[242:245], v[250:251], off offset:512
	global_load_dwordx4 v[246:249], v[250:251], off offset:528
	v_add_u32_e32 v250, 32, v158
	v_ashrrev_i32_e32 v251, 31, v250
	v_lshlrev_b64 v[250:251], 12, v[250:251]
	v_lshl_add_u64 v[250:251], s[36:37], 0, v[250:251]
	v_lshl_add_u64 v[250:251], v[250:251], 0, v[152:153]
	global_load_dwordx4 v[202:205], v[250:251], off
	global_load_dwordx4 v[206:209], v[250:251], off offset:16
	global_load_dwordx4 v[210:213], v[250:251], off offset:512
	global_load_dwordx4 v[214:217], v[250:251], off offset:528
	v_and_b32_e32 v174, 64, v176
	v_add_u32_e32 v179, 64, v174
	v_cmp_lt_i32_e32 vcc, v161, v179
	s_waitcnt vmcnt(8)
	v_pk_fma_f32 v[142:143], v[142:143], v[134:135], v[220:221]
	v_cndmask_b32_e32 v161, v176, v161, vcc
	v_pk_fma_f32 v[162:163], v[140:141], v[132:133], v[218:219]
	v_pk_fma_f32 v[138:139], v[138:139], v[130:131], v[224:225]
	v_pk_fma_f32 v[140:141], v[136:137], v[128:129], v[222:223]
	v_pk_fma_f32 v[122:123], v[122:123], v[126:127], v[228:229]
	v_pk_fma_f32 v[136:137], v[120:121], v[124:125], v[226:227]
	v_pk_fma_f32 v[114:115], v[114:115], v[118:119], v[232:233]
	v_pk_fma_f32 v[120:121], v[112:113], v[116:117], v[230:231]
	v_lshlrev_b32_e32 v177, 2, v161
	v_mul_f32_e32 v112, v163, v163
	v_mul_f32_e32 v113, v143, v143
	v_mul_f32_e32 v161, v141, v141
	v_mul_f32_e32 v164, v139, v139
	v_mul_f32_e32 v165, v137, v137
	v_mul_f32_e32 v166, v123, v123
	v_mul_f32_e32 v167, v121, v121
	v_mul_f32_e32 v168, v115, v115
	v_fmac_f32_e32 v112, v162, v162
	v_fmac_f32_e32 v113, v142, v142
	v_fmac_f32_e32 v161, v140, v140
	v_fmac_f32_e32 v164, v138, v138
	v_fmac_f32_e32 v165, v136, v136
	v_fmac_f32_e32 v166, v122, v122
	v_fmac_f32_e32 v167, v120, v120
	v_fmac_f32_e32 v168, v114, v114
	v_add_f32_e32 v112, v112, v113
	v_add_f32_e32 v113, v161, v164
	v_add_f32_e32 v161, v165, v166
	v_add_f32_e32 v164, v167, v168
	v_add_f32_e32 v112, v112, v113
	v_add_f32_e32 v113, v161, v164
	v_add_f32_e32 v112, v112, v113
	ds_bpermute_b32 v113, v177, v112
	v_xor_b32_e32 v161, 32, v176
	v_cmp_lt_i32_e32 vcc, v161, v179
	s_waitcnt lgkmcnt(0)
	v_add_f32_e32 v112, v112, v113
	v_cndmask_b32_e32 v161, v176, v161, vcc
	v_lshlrev_b32_e32 v178, 2, v161
	ds_bpermute_b32 v161, v178, v112
	v_or_b32_e32 v113, s62, v159
	v_cmp_eq_u32_e32 vcc, 0, v190
	v_lshl_add_u32 v113, v113, 4, s66
	s_and_saveexec_b64 s[4:5], vcc
	s_cbranch_execz .LBB0_1219
	s_waitcnt lgkmcnt(0)
	v_add_f32_e32 v112, v112, v161
	ds_write_b32 v113, v112
.LBB0_1219:
	s_or_b64 exec, exec, s[4:5]
	v_or_b32_e32 v112, 16, v158
	v_mov_b32_e32 v164, v112
	s_nop 0
	v_ashrrev_i32_e32 v165, 31, v164
	v_lshlrev_b64 v[164:165], 12, v[164:165]
	v_lshl_add_u64 v[164:165], s[36:37], 0, v[164:165]
	v_lshl_add_u64 v[186:187], v[164:165], 0, v[152:153]
	v_add_u32_e32 v250, 48, v158
	v_ashrrev_i32_e32 v251, 31, v250
	v_lshlrev_b64 v[250:251], 12, v[250:251]
	v_lshl_add_u64 v[250:251], s[36:37], 0, v[250:251]
	v_lshl_add_u64 v[250:251], v[250:251], 0, v[152:153]
	global_load_dwordx4 v[218:221], v[250:251], off
	global_load_dwordx4 v[222:225], v[250:251], off offset:16
	global_load_dwordx4 v[226:229], v[250:251], off offset:512
	global_load_dwordx4 v[230:233], v[250:251], off offset:528
	s_nop 0
	s_waitcnt vmcnt(8)
	v_pk_fma_f32 v[110:111], v[110:111], v[134:135], v[236:237]
	v_pk_fma_f32 v[164:165], v[108:109], v[132:133], v[234:235]
	v_pk_fma_f32 v[106:107], v[106:107], v[130:131], v[240:241]
	v_pk_fma_f32 v[108:109], v[104:105], v[128:129], v[238:239]
	v_pk_fma_f32 v[102:103], v[102:103], v[126:127], v[244:245]
	v_pk_fma_f32 v[104:105], v[100:101], v[124:125], v[242:243]
	v_pk_fma_f32 v[98:99], v[98:99], v[118:119], v[248:249]
	v_pk_fma_f32 v[100:101], v[96:97], v[116:117], v[246:247]
	v_mul_f32_e32 v96, v165, v165
	v_mul_f32_e32 v97, v111, v111
	s_waitcnt lgkmcnt(0)
	v_mul_f32_e32 v161, v109, v109
	v_mul_f32_e32 v166, v107, v107
	v_mul_f32_e32 v167, v105, v105
	v_mul_f32_e32 v168, v103, v103
	v_mul_f32_e32 v169, v101, v101
	v_mul_f32_e32 v170, v99, v99
	v_fmac_f32_e32 v96, v164, v164
	v_fmac_f32_e32 v97, v110, v110
	v_fmac_f32_e32 v161, v108, v108
	v_fmac_f32_e32 v166, v106, v106
	v_fmac_f32_e32 v167, v104, v104
	v_fmac_f32_e32 v168, v102, v102
	v_fmac_f32_e32 v169, v100, v100
	v_fmac_f32_e32 v170, v98, v98
	v_add_f32_e32 v96, v96, v97
	v_add_f32_e32 v97, v161, v166
	v_add_f32_e32 v161, v167, v168
	v_add_f32_e32 v166, v169, v170
	v_add_f32_e32 v96, v96, v97
	v_add_f32_e32 v97, v161, v166
	v_add_f32_e32 v96, v96, v97
	ds_bpermute_b32 v97, v177, v96
	s_waitcnt lgkmcnt(0)
	v_add_f32_e32 v96, v96, v97
	ds_bpermute_b32 v97, v178, v96
	s_and_saveexec_b64 s[4:5], vcc
	s_cbranch_execz .LBB0_1221
	s_waitcnt lgkmcnt(0)
	v_add_f32_e32 v96, v96, v97
	ds_write_b32 v113, v96 offset:256
;     __device__ __forceinline__ void operator()(f32x4 (&acc)[2][2][4][2], const Unit& u, int wr, int wc, int fr, int fq, LAS unsigned char* lds) const {
;     ...
;                 for (int m = 0; m < 4; ++m) { int rr_ = row0 + ai * HALF + m * 16; asm volatile("" : "+v"(rr_)); const float* xr = xp + (size_t)rr_ * DM + col0;
;                     float sq = 0.f;
; #pragma unroll
;                     for (int bj = 0; bj < 2; ++bj) { const f32x4 v0 = *(const f32x4*)(xr + bj * HALF) + gv[bj][0] * acc[ai][bj][m][0], v1 = *(const f32x4*)(xr + bj * HALF + 4) + gv[bj][1] * acc[ai][bj][m][1];
;                         acc[ai][bj][m][0] = v0; acc[ai][bj][m][1] = v1;
;                         sq += ((v0[0] * v0[0] + v0[1] * v0[1]) + (v0[2] * v0[2] + v0[3] * v0[3])) + ((v1[0] * v1[0] + v1[1] * v1[1]) + (v1[2] * v1[2] + v1[3] * v1[3])); }
;                     sq += __shfl_xor(sq, 16); sq += __shfl_xor(sq, 32);
;                     if (fq == 0) P[(ai * HALF + wr * 64 + m * 16 + fr) * 4 + wc] = sq; }
.LBB0_1221:
	s_or_b64 exec, exec, s[4:5]
	v_or_b32_e32 v96, 32, v158
	v_mov_b32_e32 v166, v96
	s_nop 0
	v_ashrrev_i32_e32 v167, 31, v166
	v_lshlrev_b64 v[166:167], 12, v[166:167]
	v_lshl_add_u64 v[166:167], s[36:37], 0, v[166:167]
	v_lshl_add_u64 v[174:175], v[166:167], 0, v[152:153]
	v_add_u32_e32 v250, 128, v158
	v_ashrrev_i32_e32 v251, 31, v250
	v_lshlrev_b64 v[250:251], 12, v[250:251]
	v_lshl_add_u64 v[250:251], s[36:37], 0, v[250:251]
	v_lshl_add_u64 v[250:251], v[250:251], 0, v[152:153]
	global_load_dwordx4 v[234:237], v[250:251], off
	global_load_dwordx4 v[238:241], v[250:251], off offset:16
	global_load_dwordx4 v[242:245], v[250:251], off offset:512
	global_load_dwordx4 v[246:249], v[250:251], off offset:528
	s_waitcnt vmcnt(8)
	v_pk_fma_f32 v[94:95], v[94:95], v[134:135], v[204:205]
	v_pk_fma_f32 v[166:167], v[92:93], v[132:133], v[202:203]
	v_pk_fma_f32 v[90:91], v[90:91], v[130:131], v[208:209]
	v_pk_fma_f32 v[92:93], v[88:89], v[128:129], v[206:207]
	v_pk_fma_f32 v[86:87], v[86:87], v[126:127], v[212:213]
	v_pk_fma_f32 v[88:89], v[84:85], v[124:125], v[210:211]
	v_pk_fma_f32 v[82:83], v[82:83], v[118:119], v[216:217]
	v_pk_fma_f32 v[84:85], v[80:81], v[116:117], v[214:215]
	v_mul_f32_e32 v80, v167, v167
	v_mul_f32_e32 v81, v95, v95
	s_waitcnt lgkmcnt(0)
	v_mul_f32_e32 v97, v93, v93
	v_mul_f32_e32 v161, v91, v91
	v_mul_f32_e32 v168, v89, v89
	v_mul_f32_e32 v169, v87, v87
	v_mul_f32_e32 v170, v85, v85
	v_mul_f32_e32 v171, v83, v83
	v_fmac_f32_e32 v80, v166, v166
	v_fmac_f32_e32 v81, v94, v94
	v_fmac_f32_e32 v97, v92, v92
	v_fmac_f32_e32 v161, v90, v90
	v_fmac_f32_e32 v168, v88, v88
	v_fmac_f32_e32 v169, v86, v86
	v_fmac_f32_e32 v170, v84, v84
	v_fmac_f32_e32 v171, v82, v82
	v_add_f32_e32 v80, v80, v81
	v_add_f32_e32 v81, v97, v161
	v_add_f32_e32 v97, v168, v169
	v_add_f32_e32 v161, v170, v171
	v_add_f32_e32 v80, v80, v81
	v_add_f32_e32 v81, v97, v161
	v_add_f32_e32 v80, v80, v81
	ds_bpermute_b32 v81, v177, v80
	s_waitcnt lgkmcnt(0)
	v_add_f32_e32 v80, v80, v81
	ds_bpermute_b32 v81, v178, v80
	s_and_saveexec_b64 s[4:5], vcc
	s_cbranch_execz .LBB0_1223
	s_waitcnt lgkmcnt(0)
	v_add_f32_e32 v80, v80, v81
	ds_write_b32 v113, v80 offset:512
.LBB0_1223:
	s_or_b64 exec, exec, s[4:5]
	v_or_b32_e32 v80, 48, v158
	v_mov_b32_e32 v168, v80
	s_nop 0
	v_ashrrev_i32_e32 v169, 31, v168
	v_lshlrev_b64 v[168:169], 12, v[168:169]
	v_lshl_add_u64 v[168:169], s[36:37], 0, v[168:169]
	v_lshl_add_u64 v[190:191], v[168:169], 0, v[152:153]
	v_add_u32_e32 v250, 144, v158
	v_ashrrev_i32_e32 v251, 31, v250
	v_lshlrev_b64 v[250:251], 12, v[250:251]
	v_lshl_add_u64 v[250:251], s[36:37], 0, v[250:251]
	v_lshl_add_u64 v[250:251], v[250:251], 0, v[152:153]
	global_load_dwordx4 v[202:205], v[250:251], off
	global_load_dwordx4 v[206:209], v[250:251], off offset:16
	global_load_dwordx4 v[210:213], v[250:251], off offset:512
	global_load_dwordx4 v[214:217], v[250:251], off offset:528
	s_nop 0
	s_waitcnt vmcnt(8)
	v_pk_fma_f32 v[78:79], v[78:79], v[134:135], v[220:221]
	v_pk_fma_f32 v[76:77], v[76:77], v[132:133], v[218:219]
	v_pk_fma_f32 v[74:75], v[74:75], v[130:131], v[224:225]
	v_pk_fma_f32 v[72:73], v[72:73], v[128:129], v[222:223]
	v_pk_fma_f32 v[70:71], v[70:71], v[126:127], v[228:229]
	v_pk_fma_f32 v[68:69], v[68:69], v[124:125], v[226:227]
	v_pk_fma_f32 v[66:67], v[66:67], v[118:119], v[232:233]
	v_pk_fma_f32 v[64:65], v[64:65], v[116:117], v[230:231]
	s_waitcnt lgkmcnt(0)
	v_mul_f32_e32 v81, v77, v77
	v_mul_f32_e32 v97, v79, v79
	v_mul_f32_e32 v161, v73, v73
	v_mul_f32_e32 v168, v75, v75
	v_mul_f32_e32 v169, v69, v69
	v_mul_f32_e32 v170, v71, v71
	v_mul_f32_e32 v171, v65, v65
	v_mul_f32_e32 v172, v67, v67
	v_fmac_f32_e32 v81, v76, v76
	v_fmac_f32_e32 v97, v78, v78
	v_fmac_f32_e32 v161, v72, v72
	v_fmac_f32_e32 v168, v74, v74
	v_fmac_f32_e32 v169, v68, v68
	v_fmac_f32_e32 v170, v70, v70
	v_fmac_f32_e32 v171, v64, v64
	v_fmac_f32_e32 v172, v66, v66
	v_add_f32_e32 v81, v81, v97
	v_add_f32_e32 v97, v161, v168
	v_add_f32_e32 v161, v169, v170
	v_add_f32_e32 v168, v171, v172
	v_add_f32_e32 v81, v81, v97
	v_add_f32_e32 v97, v161, v168
	v_add_f32_e32 v81, v81, v97
	ds_bpermute_b32 v97, v177, v81
	s_waitcnt lgkmcnt(0)
	v_add_f32_e32 v81, v81, v97
	ds_bpermute_b32 v97, v178, v81
	s_and_saveexec_b64 s[4:5], vcc
	s_cbranch_execz .LBB0_1225
	s_waitcnt lgkmcnt(0)
	v_add_f32_e32 v81, v81, v97
	ds_write_b32 v113, v81 offset:768
;     __device__ __forceinline__ void operator()(f32x4 (&acc)[2][2][4][2], const Unit& u, int wr, int wc, int fr, int fq, LAS unsigned char* lds) const {
;     ...
;                 for (int m = 0; m < 4; ++m) { int rr_ = row0 + ai * HALF + m * 16; asm volatile("" : "+v"(rr_)); const float* xr = xp + (size_t)rr_ * DM + col0;
;                     float sq = 0.f;
; #pragma unroll
;                     for (int bj = 0; bj < 2; ++bj) { const f32x4 v0 = *(const f32x4*)(xr + bj * HALF) + gv[bj][0] * acc[ai][bj][m][0], v1 = *(const f32x4*)(xr + bj * HALF + 4) + gv[bj][1] * acc[ai][bj][m][1];
;                         acc[ai][bj][m][0] = v0; acc[ai][bj][m][1] = v1;
;                         sq += ((v0[0] * v0[0] + v0[1] * v0[1]) + (v0[2] * v0[2] + v0[3] * v0[3])) + ((v1[0] * v1[0] + v1[1] * v1[1]) + (v1[2] * v1[2] + v1[3] * v1[3])); }
;                     sq += __shfl_xor(sq, 16); sq += __shfl_xor(sq, 32);
;                     if (fq == 0) P[(ai * HALF + wr * 64 + m * 16 + fr) * 4 + wc] = sq; }
.LBB0_1225:
	s_or_b64 exec, exec, s[4:5]
	v_add_u32_e32 v168, 0x80, v158
	v_mov_b32_e32 v170, v168
	s_nop 0
	v_ashrrev_i32_e32 v171, 31, v170
	v_lshlrev_b64 v[170:171], 12, v[170:171]
	v_lshl_add_u64 v[170:171], s[36:37], 0, v[170:171]
	v_lshl_add_u64 v[174:175], v[170:171], 0, v[152:153]
	v_add_u32_e32 v250, 160, v158
	v_ashrrev_i32_e32 v251, 31, v250
	v_lshlrev_b64 v[250:251], 12, v[250:251]
	v_lshl_add_u64 v[250:251], s[36:37], 0, v[250:251]
	v_lshl_add_u64 v[250:251], v[250:251], 0, v[152:153]
	global_load_dwordx4 v[218:221], v[250:251], off
	global_load_dwordx4 v[222:225], v[250:251], off offset:16
	global_load_dwordx4 v[226:229], v[250:251], off offset:512
	global_load_dwordx4 v[230:233], v[250:251], off offset:528
	s_waitcnt vmcnt(8)
	v_pk_fma_f32 v[62:63], v[62:63], v[134:135], v[236:237]
	v_pk_fma_f32 v[60:61], v[60:61], v[132:133], v[234:235]
	v_pk_fma_f32 v[58:59], v[58:59], v[130:131], v[240:241]
	v_pk_fma_f32 v[56:57], v[56:57], v[128:129], v[238:239]
	v_pk_fma_f32 v[54:55], v[54:55], v[126:127], v[244:245]
	v_pk_fma_f32 v[52:53], v[52:53], v[124:125], v[242:243]
	v_pk_fma_f32 v[50:51], v[50:51], v[118:119], v[248:249]
	v_pk_fma_f32 v[48:49], v[48:49], v[116:117], v[246:247]
	v_mul_f32_e32 v81, v61, v61
	s_waitcnt lgkmcnt(0)
	v_mul_f32_e32 v97, v63, v63
	v_mul_f32_e32 v161, v57, v57
	v_mul_f32_e32 v169, v59, v59
	v_mul_f32_e32 v170, v53, v53
	v_mul_f32_e32 v171, v55, v55
	v_mul_f32_e32 v172, v49, v49
	v_mul_f32_e32 v173, v51, v51
	v_fmac_f32_e32 v81, v60, v60
	v_fmac_f32_e32 v97, v62, v62
	v_fmac_f32_e32 v161, v56, v56
	v_fmac_f32_e32 v169, v58, v58
	v_fmac_f32_e32 v170, v52, v52
	v_fmac_f32_e32 v171, v54, v54
	v_fmac_f32_e32 v172, v48, v48
	v_fmac_f32_e32 v173, v50, v50
	v_add_f32_e32 v81, v81, v97
	v_add_f32_e32 v97, v161, v169
	v_add_f32_e32 v161, v170, v171
	v_add_f32_e32 v169, v172, v173
	v_add_f32_e32 v81, v81, v97
	v_add_f32_e32 v97, v161, v169
	v_add_f32_e32 v81, v81, v97
	ds_bpermute_b32 v97, v177, v81
	s_waitcnt lgkmcnt(0)
	v_add_f32_e32 v81, v81, v97
	ds_bpermute_b32 v97, v178, v81
	s_and_saveexec_b64 s[4:5], vcc
	s_cbranch_execz .LBB0_1227
	s_waitcnt lgkmcnt(0)
	v_add_f32_e32 v81, v81, v97
	ds_write_b32 v113, v81 offset:2048
.LBB0_1227:
	s_or_b64 exec, exec, s[4:5]
	v_add_u32_e32 v170, 0x90, v158
	v_mov_b32_e32 v172, v170
	s_nop 0
	v_ashrrev_i32_e32 v173, 31, v172
	v_lshlrev_b64 v[172:173], 12, v[172:173]
	v_lshl_add_u64 v[172:173], s[36:37], 0, v[172:173]
	v_lshl_add_u64 v[194:195], v[172:173], 0, v[152:153]
	v_add_u32_e32 v250, 176, v158
	v_ashrrev_i32_e32 v251, 31, v250
	v_lshlrev_b64 v[250:251], 12, v[250:251]
	v_lshl_add_u64 v[250:251], s[36:37], 0, v[250:251]
	v_lshl_add_u64 v[250:251], v[250:251], 0, v[152:153]
	global_load_dwordx4 v[234:237], v[250:251], off
	global_load_dwordx4 v[238:241], v[250:251], off offset:16
	global_load_dwordx4 v[242:245], v[250:251], off offset:512
	global_load_dwordx4 v[246:249], v[250:251], off offset:528
	s_nop 0
	s_waitcnt vmcnt(8)
	v_pk_fma_f32 v[46:47], v[46:47], v[134:135], v[204:205]
	v_pk_fma_f32 v[44:45], v[44:45], v[132:133], v[202:203]
	v_pk_fma_f32 v[42:43], v[42:43], v[130:131], v[208:209]
	v_pk_fma_f32 v[40:41], v[40:41], v[128:129], v[206:207]
	v_pk_fma_f32 v[38:39], v[38:39], v[126:127], v[212:213]
	v_pk_fma_f32 v[36:37], v[36:37], v[124:125], v[210:211]
	v_pk_fma_f32 v[34:35], v[34:35], v[118:119], v[216:217]
	v_pk_fma_f32 v[32:33], v[32:33], v[116:117], v[214:215]
	v_mul_f32_e32 v81, v45, v45
	s_waitcnt lgkmcnt(0)
	v_mul_f32_e32 v97, v47, v47
	v_mul_f32_e32 v161, v41, v41
	v_mul_f32_e32 v169, v43, v43
	v_mul_f32_e32 v171, v37, v37
	v_mul_f32_e32 v172, v39, v39
	v_mul_f32_e32 v173, v33, v33
	v_mul_f32_e32 v174, v35, v35
	v_fmac_f32_e32 v81, v44, v44
	v_fmac_f32_e32 v97, v46, v46
	v_fmac_f32_e32 v161, v40, v40
	v_fmac_f32_e32 v169, v42, v42
	v_fmac_f32_e32 v171, v36, v36
	v_fmac_f32_e32 v172, v38, v38
	v_fmac_f32_e32 v173, v32, v32
	v_fmac_f32_e32 v174, v34, v34
	v_add_f32_e32 v81, v81, v97
	v_add_f32_e32 v97, v161, v169
	v_add_f32_e32 v161, v171, v172
	v_add_f32_e32 v169, v173, v174
	v_add_f32_e32 v81, v81, v97
	v_add_f32_e32 v97, v161, v169
	v_add_f32_e32 v81, v81, v97
	ds_bpermute_b32 v97, v177, v81
	s_waitcnt lgkmcnt(0)
	v_add_f32_e32 v81, v81, v97
	ds_bpermute_b32 v97, v178, v81
	s_and_saveexec_b64 s[4:5], vcc
	s_cbranch_execz .LBB0_1229
	s_waitcnt lgkmcnt(0)
	v_add_f32_e32 v81, v81, v97
	ds_write_b32 v113, v81 offset:2304
.LBB0_1229:
	s_or_b64 exec, exec, s[4:5]
	v_add_u32_e32 v172, 0xa0, v158
	v_mov_b32_e32 v174, v172
	s_nop 0
	v_ashrrev_i32_e32 v175, 31, v174
	v_lshlrev_b64 v[174:175], 12, v[174:175]
	v_lshl_add_u64 v[174:175], s[36:37], 0, v[174:175]
	v_lshl_add_u64 v[174:175], v[174:175], 0, v[152:153]
	s_waitcnt vmcnt(4)
	v_pk_fma_f32 v[30:31], v[30:31], v[134:135], v[220:221]
	v_pk_fma_f32 v[28:29], v[28:29], v[132:133], v[218:219]
	v_pk_fma_f32 v[26:27], v[26:27], v[130:131], v[224:225]
	v_pk_fma_f32 v[24:25], v[24:25], v[128:129], v[222:223]
	v_pk_fma_f32 v[22:23], v[22:23], v[126:127], v[228:229]
	v_pk_fma_f32 v[20:21], v[20:21], v[124:125], v[226:227]
	v_pk_fma_f32 v[18:19], v[18:19], v[118:119], v[232:233]
	v_pk_fma_f32 v[16:17], v[16:17], v[116:117], v[230:231]
	v_mul_f32_e32 v81, v29, v29
	s_waitcnt lgkmcnt(0)
	v_mul_f32_e32 v97, v31, v31
	v_mul_f32_e32 v161, v25, v25
	v_mul_f32_e32 v169, v27, v27
	v_mul_f32_e32 v171, v21, v21
	v_mul_f32_e32 v173, v23, v23
	v_mul_f32_e32 v174, v17, v17
	v_mul_f32_e32 v175, v19, v19
	v_fmac_f32_e32 v81, v28, v28
	v_fmac_f32_e32 v97, v30, v30
	v_fmac_f32_e32 v161, v24, v24
	v_fmac_f32_e32 v169, v26, v26
	v_fmac_f32_e32 v171, v20, v20
	v_fmac_f32_e32 v173, v22, v22
	v_fmac_f32_e32 v174, v16, v16
	v_fmac_f32_e32 v175, v18, v18
	v_add_f32_e32 v81, v81, v97
	v_add_f32_e32 v97, v161, v169
	v_add_f32_e32 v161, v171, v173
	v_add_f32_e32 v169, v174, v175
	v_add_f32_e32 v81, v81, v97
	v_add_f32_e32 v97, v161, v169
	v_add_f32_e32 v81, v81, v97
	ds_bpermute_b32 v97, v177, v81
	s_waitcnt lgkmcnt(0)
	v_add_f32_e32 v81, v81, v97
	ds_bpermute_b32 v97, v178, v81
	s_and_saveexec_b64 s[4:5], vcc
	s_cbranch_execz .LBB0_1231
	s_waitcnt lgkmcnt(0)
	v_add_f32_e32 v81, v81, v97
	ds_write_b32 v113, v81 offset:2560
